# v31 + pool unit: MFMA operand reads prefetched, sliding-window LDS reads hoisted per 4-row iteration
# baseline (speedup 1.0000x reference)
; #define LAS __attribute__((address_space(3)))
; __device__ __forceinline__ void pool_unit(LAS char* lds, int pm, int g, bf16_t* Z, const bf16_t* Wt  , const float* pscale, bool dry) {
;     ...
;     for (int k = 0; k < 4; ++k) { const int i = tid + 512 * k; *(LAS u32x4*)(U + (i >> 4) * PP + (i & 15) * 16) = wv[k]; }
;     __syncthreads();
;     f32x16 acc[4] = {};
; #pragma unroll
;     for (int s = 0; s < 8; ++s) {
;         const bf16x8 a = *(const LAS bf16x8*)(lds + (32 * wid + r32) * PP + (16 * s + 8 * hi) * 2);
; #pragma unroll
;         for (int n = 0; n < 4; ++n) {
;             const bf16x8 bw = *(const LAS bf16x8*)(U + (32 * n + r32) * PP + (16 * s + 8 * hi) * 2);
;             acc[n] = __builtin_amdgcn_mfma_f32_32x32x16_bf16(a, bw, acc[n], 0, 0, 0);
;         }
;     }
.LBB0_659:
	v_mad_u64_u32 v[18:19], s[0:1], v38, s58, v[46:47]
	s_waitcnt lgkmcnt(0)
	s_barrier
	s_waitcnt vmcnt(3)
	ds_write_b128 v18, v[6:9]
	v_mad_u64_u32 v[6:7], s[0:1], v40, s58, v[46:47]
	s_waitcnt vmcnt(2)
	ds_write_b128 v6, v[2:5]
	v_mad_u64_u32 v[2:3], s[0:1], v42, s58, v[46:47]
	s_waitcnt vmcnt(1)
	ds_write_b128 v2, v[14:17]
	v_mad_u64_u32 v[2:3], s[0:1], v44, s58, v[46:47]
	s_ashr_i32 s1, s17, 1
	s_waitcnt vmcnt(0)
	ds_write_b128 v2, v[10:13]
	s_and_b32 s0, s1, 0xffffffe0
	v_mov_b32_e32 v2, s1
	s_movk_i32 s1, 0xffe0
	v_bfe_u32 v0, v67, 5, 1
	v_bfi_b32 v2, s1, v2, v67
	v_mul_lo_u32 v2, v2, s58
	v_lshlrev_b32_e32 v69, 4, v0
	v_readlane_b32 s1, v254, 45
	v_and_b32_e32 v68, 31, v67
	v_add3_u32 v79, 0, v2, v69
	v_mov_b32_e32 v2, s1
	v_mad_u32_u24 v80, v68, s58, v2
	v_add_u32_e32 v10, v80, v69
	s_waitcnt lgkmcnt(0)
	s_barrier
	v_mov_b32_e32 v77, v10
	ds_read_b128 v[114:117], v79
	ds_read_b128 v[146:149], v77
	ds_read_b128 v[150:153], v77 offset:8704
	ds_read_b128 v[154:157], v77 offset:17408
	ds_read_b128 v[158:161], v77 offset:26112
	ds_read_b128 v[118:121], v79 offset:32
	ds_read_b128 v[162:165], v77 offset:32
	ds_read_b128 v[166:169], v77 offset:8736
	ds_read_b128 v[170:173], v77 offset:17440
	s_waitcnt lgkmcnt(8)
	s_waitcnt lgkmcnt(7)
	v_mfma_f32_32x32x16_bf16 v[50:65], v[114:117], v[146:149], 0
	ds_read_b128 v[174:177], v77 offset:26144
	s_waitcnt lgkmcnt(7)
	v_mfma_f32_32x32x16_bf16 v[34:49], v[114:117], v[150:153], 0
	ds_read_b128 v[122:125], v79 offset:64
	s_waitcnt lgkmcnt(7)
	v_mfma_f32_32x32x16_bf16 v[18:33], v[114:117], v[154:157], 0
	ds_read_b128 v[146:149], v77 offset:64
	s_waitcnt lgkmcnt(7)
	v_mfma_f32_32x32x16_bf16 v[2:17], v[114:117], v[158:161], 0
	ds_read_b128 v[150:153], v77 offset:8768
	s_waitcnt lgkmcnt(7)
	s_waitcnt lgkmcnt(6)
	v_mfma_f32_32x32x16_bf16 v[50:65], v[118:121], v[162:165], v[50:65]
	ds_read_b128 v[154:157], v77 offset:17472
	s_waitcnt lgkmcnt(6)
	v_mfma_f32_32x32x16_bf16 v[34:49], v[118:121], v[166:169], v[34:49]
	ds_read_b128 v[158:161], v77 offset:26176
	s_waitcnt lgkmcnt(6)
	v_mfma_f32_32x32x16_bf16 v[18:33], v[118:121], v[170:173], v[18:33]
	ds_read_b128 v[126:129], v79 offset:96
	s_waitcnt lgkmcnt(6)
	v_mfma_f32_32x32x16_bf16 v[2:17], v[118:121], v[174:177], v[2:17]
	ds_read_b128 v[162:165], v77 offset:96
	s_waitcnt lgkmcnt(6)
	s_waitcnt lgkmcnt(5)
	v_mfma_f32_32x32x16_bf16 v[50:65], v[122:125], v[146:149], v[50:65]
	ds_read_b128 v[166:169], v77 offset:8800
	s_waitcnt lgkmcnt(5)
	v_mfma_f32_32x32x16_bf16 v[34:49], v[122:125], v[150:153], v[34:49]
	ds_read_b128 v[170:173], v77 offset:17504
	s_waitcnt lgkmcnt(5)
	v_mfma_f32_32x32x16_bf16 v[18:33], v[122:125], v[154:157], v[18:33]
	ds_read_b128 v[174:177], v77 offset:26208
	s_waitcnt lgkmcnt(5)
	v_mfma_f32_32x32x16_bf16 v[2:17], v[122:125], v[158:161], v[2:17]
	ds_read_b128 v[130:133], v79 offset:128
	s_waitcnt lgkmcnt(5)
	s_waitcnt lgkmcnt(4)
	v_mfma_f32_32x32x16_bf16 v[50:65], v[126:129], v[162:165], v[50:65]
	ds_read_b128 v[146:149], v77 offset:128
	s_waitcnt lgkmcnt(4)
	v_mfma_f32_32x32x16_bf16 v[34:49], v[126:129], v[166:169], v[34:49]
	ds_read_b128 v[150:153], v77 offset:8832
	s_waitcnt lgkmcnt(4)
	v_mfma_f32_32x32x16_bf16 v[18:33], v[126:129], v[170:173], v[18:33]
	ds_read_b128 v[154:157], v77 offset:17536
	s_waitcnt lgkmcnt(4)
	v_mfma_f32_32x32x16_bf16 v[2:17], v[126:129], v[174:177], v[2:17]
	ds_read_b128 v[158:161], v77 offset:26240
	s_waitcnt lgkmcnt(4)
	s_waitcnt lgkmcnt(3)
	v_mfma_f32_32x32x16_bf16 v[50:65], v[130:133], v[146:149], v[50:65]
	ds_read_b128 v[134:137], v79 offset:160
	s_waitcnt lgkmcnt(3)
	v_mfma_f32_32x32x16_bf16 v[34:49], v[130:133], v[150:153], v[34:49]
	ds_read_b128 v[162:165], v77 offset:160
	s_waitcnt lgkmcnt(3)
	v_mfma_f32_32x32x16_bf16 v[18:33], v[130:133], v[154:157], v[18:33]
	ds_read_b128 v[166:169], v77 offset:8864
	s_waitcnt lgkmcnt(3)
	v_mfma_f32_32x32x16_bf16 v[2:17], v[130:133], v[158:161], v[2:17]
	ds_read_b128 v[170:173], v77 offset:17568
	s_waitcnt lgkmcnt(3)
	s_waitcnt lgkmcnt(2)
	v_mfma_f32_32x32x16_bf16 v[50:65], v[134:137], v[162:165], v[50:65]
	ds_read_b128 v[174:177], v77 offset:26272
	s_waitcnt lgkmcnt(2)
	v_mfma_f32_32x32x16_bf16 v[34:49], v[134:137], v[166:169], v[34:49]
	ds_read_b128 v[138:141], v79 offset:192
	s_waitcnt lgkmcnt(2)
	v_mfma_f32_32x32x16_bf16 v[18:33], v[134:137], v[170:173], v[18:33]
	ds_read_b128 v[146:149], v77 offset:192
	s_waitcnt lgkmcnt(2)
	v_mfma_f32_32x32x16_bf16 v[2:17], v[134:137], v[174:177], v[2:17]
	ds_read_b128 v[150:153], v77 offset:8896
	s_waitcnt lgkmcnt(2)
	s_waitcnt lgkmcnt(1)
	v_mfma_f32_32x32x16_bf16 v[50:65], v[138:141], v[146:149], v[50:65]
	ds_read_b128 v[154:157], v77 offset:17600
	s_waitcnt lgkmcnt(1)
	v_mfma_f32_32x32x16_bf16 v[34:49], v[138:141], v[150:153], v[34:49]
	ds_read_b128 v[158:161], v77 offset:26304
	s_waitcnt lgkmcnt(1)
	v_mfma_f32_32x32x16_bf16 v[18:33], v[138:141], v[154:157], v[18:33]
	ds_read_b128 v[142:145], v79 offset:224
	s_waitcnt lgkmcnt(1)
	v_mfma_f32_32x32x16_bf16 v[2:17], v[138:141], v[158:161], v[2:17]
	ds_read_b128 v[162:165], v77 offset:224
	s_waitcnt lgkmcnt(1)
	s_waitcnt lgkmcnt(0)
	v_mfma_f32_32x32x16_bf16 v[50:65], v[142:145], v[162:165], v[50:65]
	ds_read_b128 v[166:169], v77 offset:8928
	s_waitcnt lgkmcnt(0)
	v_mfma_f32_32x32x16_bf16 v[34:49], v[142:145], v[166:169], v[34:49]
	ds_read_b128 v[170:173], v77 offset:17632
	s_waitcnt lgkmcnt(0)
	v_mfma_f32_32x32x16_bf16 v[18:33], v[142:145], v[170:173], v[18:33]
	ds_read_b128 v[174:177], v77 offset:26336
	s_waitcnt lgkmcnt(0)
; #define LAS __attribute__((address_space(3)))
; __device__ __forceinline__ bf16_t f2bf(float f) { return (bf16_t)(cvtpk(f, 0.f) & 0xffffu); }
; __device__ __forceinline__ int crow(int r, int hi) { return (r & 3) + 8 * (r >> 2) + 4 * hi; }
; __device__ __forceinline__ void pool_unit(LAS char* lds, int pm, int g, bf16_t* Z, const bf16_t* Wt  , const float* pscale, bool dry) {
;     ...
;     for (int s = 0; s < 8; ++s) {
;         const bf16x8 a = *(const LAS bf16x8*)(lds + (32 * wid + r32) * PP + (16 * s + 8 * hi) * 2);
; #pragma unroll
;         for (int n = 0; n < 4; ++n) {
;             const bf16x8 bw = *(const LAS bf16x8*)(U + (32 * n + r32) * PP + (16 * s + 8 * hi) * 2);
;             acc[n] = __builtin_amdgcn_mfma_f32_32x32x16_bf16(a, bw, acc[n], 0, 0, 0);
;         }
;     }
; #pragma unroll
;     for (int n = 0; n < 4; ++n) { const float sc = pscale[g * 128 + 32 * n + r32];
; #pragma unroll
;         for (int r = 0; r < 16; ++r) ((LAS bf16_t*)lds)[(32 * wid + crow(r, hi)) * (PP / 2) + 32 * n + r32] = f2bf(acc[n][r] * sc); }
;     asm volatile("s_waitcnt lgkmcnt(0)" ::: "memory");
; #pragma unroll
;     for (int i = 0; i < 8; ++i) { const int id = lane + 64 * i, row = id >> 4, ch = id & 15;
;         const u32x4 ov = *(const LAS u32x4*)(lds + (32 * wid + row) * PP + ch * 16);
;         bf16_t* yp = Z + (size_t)(pm * 256 + 32 * wid + row) * ZP + ZYP + g * 128 + ch * 8;
;         if (!dry) { const u32x4 gv = *(const u32x4*)yp; u32x4 w;
	v_mfma_f32_32x32x16_bf16 v[2:17], v[142:145], v[174:177], v[2:17]
	v_or_b32_e32 v81, 32, v69
	v_add_u32_e32 v74, v80, v81
	v_mul_u32_u24_e32 v78, 0x110, v68
	v_add3_u32 v81, s1, v81, v78
	v_lshl_or_b32 v0, v0, 2, s0
	v_mul_lo_u32 v0, v0, s58
	s_movk_i32 s17, 0x1000
	v_or_b32_e32 v81, 64, v69
	v_add_u32_e32 v74, v80, v81
	v_add3_u32 v81, s1, v81, v78
	v_or_b32_e32 v81, 0x60, v69
	v_add_u32_e32 v74, v80, v81
	v_add3_u32 v81, s1, v81, v78
	v_or_b32_e32 v81, 0x80, v69
	v_add_u32_e32 v74, v80, v81
	v_add3_u32 v81, s1, v81, v78
	v_or_b32_e32 v81, 0xa0, v69
	v_add_u32_e32 v74, v80, v81
	v_add3_u32 v81, s1, v81, v78
	v_or_b32_e32 v81, 0xc0, v69
	v_or_b32_e32 v69, 0xe0, v69
	v_add_u32_e32 v74, v80, v81
	v_add3_u32 v81, s1, v81, v78
	v_add_u32_e32 v74, v80, v69
	v_add3_u32 v69, s1, v69, v78
	s_add_i32 s1, s0, s8
	s_lshl_b32 s8, s2, 1
	v_or_b32_e32 v69, s2, v68
	v_lshlrev_b32_e32 v70, 1, v68
	v_lshlrev_b32_e32 v68, 2, v69
	global_load_dword v69, v68, s[56:57]
	global_load_dword v162, v68, s[56:57] offset:128
	global_load_dword v163, v68, s[56:57] offset:256
	global_load_dword v164, v68, s[56:57] offset:384
	v_bfe_u32 v166, v67, 4, 2
	v_mov_b64_e32 v[168:169], s[88:89]
	v_mov_b32_e32 v170, v66
	v_mov_b32_e32 v171, 0
	v_or_b32_e32 v167, s1, v166
	v_mad_i64_i32 v[146:147], s[24:25], v167, s13, v[168:169]
	v_lshl_add_u64 v[146:147], v[146:147], 0, s[8:9]
	v_lshl_add_u64 v[146:147], v[146:147], 0, v[170:171]
	v_add_co_u32_e32 v146, vcc, s17, v146
	s_nop 1
	v_addc_co_u32_e32 v147, vcc, 0, v147, vcc
	global_load_dwordx4 v[114:117], v[146:147], off offset:1024
	v_or_b32_e32 v167, 4, v166
	v_or_b32_e32 v167, s1, v167
	v_mad_i64_i32 v[148:149], s[24:25], v167, s13, v[168:169]
	v_lshl_add_u64 v[148:149], v[148:149], 0, s[8:9]
	v_lshl_add_u64 v[148:149], v[148:149], 0, v[170:171]
	v_add_co_u32_e32 v148, vcc, s17, v148
	s_nop 1
	v_addc_co_u32_e32 v149, vcc, 0, v149, vcc
	global_load_dwordx4 v[118:121], v[148:149], off offset:1024
	v_or_b32_e32 v167, 8, v166
	v_or_b32_e32 v167, s1, v167
	v_mad_i64_i32 v[150:151], s[24:25], v167, s13, v[168:169]
	v_lshl_add_u64 v[150:151], v[150:151], 0, s[8:9]
	v_lshl_add_u64 v[150:151], v[150:151], 0, v[170:171]
	v_add_co_u32_e32 v150, vcc, s17, v150
	s_nop 1
	v_addc_co_u32_e32 v151, vcc, 0, v151, vcc
	global_load_dwordx4 v[122:125], v[150:151], off offset:1024
	v_or_b32_e32 v167, 12, v166
	v_or_b32_e32 v167, s1, v167
	v_mad_i64_i32 v[152:153], s[24:25], v167, s13, v[168:169]
	v_lshl_add_u64 v[152:153], v[152:153], 0, s[8:9]
	v_lshl_add_u64 v[152:153], v[152:153], 0, v[170:171]
	v_add_co_u32_e32 v152, vcc, s17, v152
	s_nop 1
	v_addc_co_u32_e32 v153, vcc, 0, v153, vcc
	global_load_dwordx4 v[126:129], v[152:153], off offset:1024
	v_or_b32_e32 v167, 16, v166
	v_or_b32_e32 v167, s1, v167
	v_mad_i64_i32 v[154:155], s[24:25], v167, s13, v[168:169]
	v_lshl_add_u64 v[154:155], v[154:155], 0, s[8:9]
	v_lshl_add_u64 v[154:155], v[154:155], 0, v[170:171]
	v_add_co_u32_e32 v154, vcc, s17, v154
	s_nop 1
	v_addc_co_u32_e32 v155, vcc, 0, v155, vcc
	global_load_dwordx4 v[130:133], v[154:155], off offset:1024
	v_or_b32_e32 v167, 20, v166
	v_or_b32_e32 v167, s1, v167
	v_mad_i64_i32 v[156:157], s[24:25], v167, s13, v[168:169]
	v_lshl_add_u64 v[156:157], v[156:157], 0, s[8:9]
	v_lshl_add_u64 v[156:157], v[156:157], 0, v[170:171]
	v_add_co_u32_e32 v156, vcc, s17, v156
	s_nop 1
	v_addc_co_u32_e32 v157, vcc, 0, v157, vcc
	global_load_dwordx4 v[134:137], v[156:157], off offset:1024
	v_or_b32_e32 v167, 24, v166
	v_or_b32_e32 v167, s1, v167
	v_mad_i64_i32 v[158:159], s[24:25], v167, s13, v[168:169]
	v_lshl_add_u64 v[158:159], v[158:159], 0, s[8:9]
	v_lshl_add_u64 v[158:159], v[158:159], 0, v[170:171]
	v_add_co_u32_e32 v158, vcc, s17, v158
	s_nop 1
	v_addc_co_u32_e32 v159, vcc, 0, v159, vcc
	global_load_dwordx4 v[138:141], v[158:159], off offset:1024
	v_or_b32_e32 v167, 28, v166
	v_or_b32_e32 v167, s1, v167
	v_mad_i64_i32 v[160:161], s[24:25], v167, s13, v[168:169]
	v_lshl_add_u64 v[160:161], v[160:161], 0, s[8:9]
	v_lshl_add_u64 v[160:161], v[160:161], 0, v[170:171]
	v_add_co_u32_e32 v160, vcc, s17, v160
	s_nop 1
	v_addc_co_u32_e32 v161, vcc, 0, v161, vcc
	global_load_dwordx4 v[142:145], v[160:161], off offset:1024
	v_add3_u32 v0, 0, v70, v0
	s_waitcnt vmcnt(11)
	v_mul_f32_e32 v50, v50, v69
	v_cvt_pk_bf16_f32 v50, v50, s0
	ds_write_b16 v0, v50
	v_mul_f32_e32 v50, v51, v69
	v_cvt_pk_bf16_f32 v50, v50, s0
	ds_write_b16 v0, v50 offset:272
	v_mul_f32_e32 v50, v52, v69
	v_cvt_pk_bf16_f32 v50, v50, s0
	ds_write_b16 v0, v50 offset:544
	v_mul_f32_e32 v50, v53, v69
	v_cvt_pk_bf16_f32 v50, v50, s0
	ds_write_b16 v0, v50 offset:816
	v_mul_f32_e32 v50, v54, v69
	v_cvt_pk_bf16_f32 v50, v50, s0
	ds_write_b16 v0, v50 offset:2176
	v_mul_f32_e32 v50, v55, v69
	v_cvt_pk_bf16_f32 v50, v50, s0
	ds_write_b16 v0, v50 offset:2448
	v_mul_f32_e32 v50, v56, v69
	v_cvt_pk_bf16_f32 v50, v50, s0
	ds_write_b16 v0, v50 offset:2720
	v_mul_f32_e32 v50, v57, v69
	v_cvt_pk_bf16_f32 v50, v50, s0
	ds_write_b16 v0, v50 offset:2992
	v_mul_f32_e32 v50, v58, v69
	v_cvt_pk_bf16_f32 v50, v50, s0
	ds_write_b16 v0, v50 offset:4352
	v_mul_f32_e32 v50, v59, v69
	v_cvt_pk_bf16_f32 v50, v50, s0
	ds_write_b16 v0, v50 offset:4624
	v_mul_f32_e32 v50, v60, v69
	v_cvt_pk_bf16_f32 v50, v50, s0
	ds_write_b16 v0, v50 offset:4896
	v_mul_f32_e32 v50, v61, v69
	v_cvt_pk_bf16_f32 v50, v50, s0
	ds_write_b16 v0, v50 offset:5168
	v_mul_f32_e32 v50, v62, v69
	v_cvt_pk_bf16_f32 v50, v50, s0
	ds_write_b16 v0, v50 offset:6528
	v_mul_f32_e32 v50, v63, v69
	v_cvt_pk_bf16_f32 v50, v50, s0
	ds_write_b16 v0, v50 offset:6800
	v_mul_f32_e32 v50, v64, v69
	v_cvt_pk_bf16_f32 v50, v50, s0
	ds_write_b16 v0, v50 offset:7072
	v_mul_f32_e32 v50, v65, v69
	v_cvt_pk_bf16_f32 v50, v50, s0
	ds_write_b16 v0, v50 offset:7344
	s_waitcnt vmcnt(10)
; #define LAS __attribute__((address_space(3)))
; __device__ __forceinline__ bf16_t f2bf(float f) { return (bf16_t)(cvtpk(f, 0.f) & 0xffffu); }
; __device__ __forceinline__ int crow(int r, int hi) { return (r & 3) + 8 * (r >> 2) + 4 * hi; }
; __device__ __forceinline__ void pool_unit(LAS char* lds, int pm, int g, bf16_t* Z, const bf16_t* Wt  , const float* pscale, bool dry) {
;     ...
; #pragma unroll
;     for (int n = 0; n < 4; ++n) { const float sc = pscale[g * 128 + 32 * n + r32];
; #pragma unroll
;         for (int r = 0; r < 16; ++r) ((LAS bf16_t*)lds)[(32 * wid + crow(r, hi)) * (PP / 2) + 32 * n + r32] = f2bf(acc[n][r] * sc); }
;     asm volatile("s_waitcnt lgkmcnt(0)" ::: "memory");
; #pragma unroll
;     for (int i = 0; i < 8; ++i) { const int id = lane + 64 * i, row = id >> 4, ch = id & 15;
;         const u32x4 ov = *(const LAS u32x4*)(lds + (32 * wid + row) * PP + ch * 16);
;         bf16_t* yp = Z + (size_t)(pm * 256 + 32 * wid + row) * ZP + ZYP + g * 128 + ch * 8;
;         if (!dry) { const u32x4 gv = *(const u32x4*)yp; u32x4 w;
	v_mov_b32_e32 v50, v162
	v_mul_f32_e32 v34, v34, v50
	v_cvt_pk_bf16_f32 v34, v34, s0
	ds_write_b16 v0, v34 offset:64
	v_mul_f32_e32 v34, v35, v50
	v_cvt_pk_bf16_f32 v34, v34, s0
	ds_write_b16 v0, v34 offset:336
	v_mul_f32_e32 v34, v36, v50
	v_cvt_pk_bf16_f32 v34, v34, s0
	ds_write_b16 v0, v34 offset:608
	v_mul_f32_e32 v34, v37, v50
	v_cvt_pk_bf16_f32 v34, v34, s0
	ds_write_b16 v0, v34 offset:880
	v_mul_f32_e32 v34, v38, v50
	v_cvt_pk_bf16_f32 v34, v34, s0
	ds_write_b16 v0, v34 offset:2240
	v_mul_f32_e32 v34, v39, v50
	v_cvt_pk_bf16_f32 v34, v34, s0
	ds_write_b16 v0, v34 offset:2512
	v_mul_f32_e32 v34, v40, v50
	v_cvt_pk_bf16_f32 v34, v34, s0
	ds_write_b16 v0, v34 offset:2784
	v_mul_f32_e32 v34, v41, v50
	v_cvt_pk_bf16_f32 v34, v34, s0
	ds_write_b16 v0, v34 offset:3056
	v_mul_f32_e32 v34, v42, v50
	v_cvt_pk_bf16_f32 v34, v34, s0
	ds_write_b16 v0, v34 offset:4416
	v_mul_f32_e32 v34, v43, v50
	v_cvt_pk_bf16_f32 v34, v34, s0
	ds_write_b16 v0, v34 offset:4688
	v_mul_f32_e32 v34, v44, v50
	v_cvt_pk_bf16_f32 v34, v34, s0
	ds_write_b16 v0, v34 offset:4960
	v_mul_f32_e32 v34, v45, v50
	v_cvt_pk_bf16_f32 v34, v34, s0
	ds_write_b16 v0, v34 offset:5232
	v_mul_f32_e32 v34, v46, v50
	v_cvt_pk_bf16_f32 v34, v34, s0
	ds_write_b16 v0, v34 offset:6592
	v_mul_f32_e32 v34, v47, v50
	v_cvt_pk_bf16_f32 v34, v34, s0
	ds_write_b16 v0, v34 offset:6864
	v_mul_f32_e32 v34, v48, v50
	v_cvt_pk_bf16_f32 v34, v34, s0
	ds_write_b16 v0, v34 offset:7136
	v_mul_f32_e32 v34, v49, v50
	v_cvt_pk_bf16_f32 v34, v34, s0
	ds_write_b16 v0, v34 offset:7408
	s_waitcnt vmcnt(9)
	v_mov_b32_e32 v34, v163
	v_mul_f32_e32 v18, v18, v34
	v_cvt_pk_bf16_f32 v18, v18, s0
	ds_write_b16 v0, v18 offset:128
	v_mul_f32_e32 v18, v19, v34
	v_cvt_pk_bf16_f32 v18, v18, s0
	ds_write_b16 v0, v18 offset:400
	v_mul_f32_e32 v18, v20, v34
	v_cvt_pk_bf16_f32 v18, v18, s0
	ds_write_b16 v0, v18 offset:672
	v_mul_f32_e32 v18, v21, v34
	v_cvt_pk_bf16_f32 v18, v18, s0
	ds_write_b16 v0, v18 offset:944
	v_mul_f32_e32 v18, v22, v34
	v_cvt_pk_bf16_f32 v18, v18, s0
	ds_write_b16 v0, v18 offset:2304
	v_mul_f32_e32 v18, v23, v34
	v_cvt_pk_bf16_f32 v18, v18, s0
	ds_write_b16 v0, v18 offset:2576
	v_mul_f32_e32 v18, v24, v34
	v_cvt_pk_bf16_f32 v18, v18, s0
	ds_write_b16 v0, v18 offset:2848
	v_mul_f32_e32 v18, v25, v34
	v_cvt_pk_bf16_f32 v18, v18, s0
	ds_write_b16 v0, v18 offset:3120
	v_mul_f32_e32 v18, v26, v34
	v_cvt_pk_bf16_f32 v18, v18, s0
	ds_write_b16 v0, v18 offset:4480
	v_mul_f32_e32 v18, v27, v34
	v_cvt_pk_bf16_f32 v18, v18, s0
	ds_write_b16 v0, v18 offset:4752
	v_mul_f32_e32 v18, v28, v34
	v_cvt_pk_bf16_f32 v18, v18, s0
	ds_write_b16 v0, v18 offset:5024
	v_mul_f32_e32 v18, v29, v34
	v_cvt_pk_bf16_f32 v18, v18, s0
	ds_write_b16 v0, v18 offset:5296
	v_mul_f32_e32 v18, v30, v34
	v_cvt_pk_bf16_f32 v18, v18, s0
	ds_write_b16 v0, v18 offset:6656
	v_mul_f32_e32 v18, v31, v34
	v_cvt_pk_bf16_f32 v18, v18, s0
	ds_write_b16 v0, v18 offset:6928
	v_mul_f32_e32 v18, v32, v34
	v_cvt_pk_bf16_f32 v18, v18, s0
	ds_write_b16 v0, v18 offset:7200
	v_mul_f32_e32 v18, v33, v34
	v_cvt_pk_bf16_f32 v18, v18, s0
	ds_write_b16 v0, v18 offset:7472
	s_waitcnt vmcnt(8)
	v_mov_b32_e32 v18, v164
	v_mul_f32_e32 v2, v2, v18
	v_cvt_pk_bf16_f32 v2, v2, s0
	ds_write_b16 v0, v2 offset:192
	v_mul_f32_e32 v2, v3, v18
	v_cvt_pk_bf16_f32 v2, v2, s0
	ds_write_b16 v0, v2 offset:464
	v_mul_f32_e32 v2, v4, v18
	v_cvt_pk_bf16_f32 v2, v2, s0
	ds_write_b16 v0, v2 offset:736
	v_mul_f32_e32 v2, v5, v18
	v_cvt_pk_bf16_f32 v2, v2, s0
	ds_write_b16 v0, v2 offset:1008
	v_mul_f32_e32 v2, v6, v18
	v_cvt_pk_bf16_f32 v2, v2, s0
	ds_write_b16 v0, v2 offset:2368
	v_mul_f32_e32 v2, v7, v18
	v_cvt_pk_bf16_f32 v2, v2, s0
	ds_write_b16 v0, v2 offset:2640
	v_mul_f32_e32 v2, v8, v18
	v_cvt_pk_bf16_f32 v2, v2, s0
	ds_write_b16 v0, v2 offset:2912
	v_mul_f32_e32 v2, v9, v18
	v_cvt_pk_bf16_f32 v2, v2, s0
	ds_write_b16 v0, v2 offset:3184
	v_mul_f32_e32 v2, v10, v18
	v_cvt_pk_bf16_f32 v2, v2, s0
	ds_write_b16 v0, v2 offset:4544
	v_mul_f32_e32 v2, v11, v18
	v_cvt_pk_bf16_f32 v2, v2, s0
	ds_write_b16 v0, v2 offset:4816
	v_mul_f32_e32 v2, v12, v18
	v_cvt_pk_bf16_f32 v2, v2, s0
	ds_write_b16 v0, v2 offset:5088
	v_mul_f32_e32 v2, v13, v18
	v_cvt_pk_bf16_f32 v2, v2, s0
	ds_write_b16 v0, v2 offset:5360
	v_mul_f32_e32 v2, v14, v18
	v_cvt_pk_bf16_f32 v2, v2, s0
	ds_write_b16 v0, v2 offset:6720
	v_mul_f32_e32 v2, v15, v18
	v_cvt_pk_bf16_f32 v2, v2, s0
	ds_write_b16 v0, v2 offset:6992
	v_mul_f32_e32 v2, v16, v18
	v_cvt_pk_bf16_f32 v2, v2, s0
	ds_write_b16 v0, v2 offset:7264
	v_mul_f32_e32 v2, v17, v18
	v_cvt_pk_bf16_f32 v2, v2, s0
	v_bfe_u32 v4, v67, 4, 2
	ds_write_b16 v0, v2 offset:7536
	v_or_b32_e32 v5, s1, v4
	v_mov_b64_e32 v[2:3], s[88:89]
	v_mad_i64_i32 v[6:7], s[24:25], v5, s13, v[2:3]
	v_lshl_add_u64 v[6:7], v[6:7], 0, s[8:9]
	v_mov_b32_e32 v67, v1
	v_lshl_add_u64 v[10:11], v[6:7], 0, v[66:67]
	v_add_co_u32_e32 v14, vcc, s17, v10
	s_waitcnt lgkmcnt(0)
	v_add_u32_e32 v0, 0, v66
	s_nop 0
	v_addc_co_u32_e32 v15, vcc, 0, v11, vcc
	s_nop 0
	v_or_b32_e32 v5, s0, v4
	v_mad_u64_u32 v[6:7], s[2:3], v5, s58, v[0:1]
	ds_read_b128 v[6:9], v6
	v_or_b32_e32 v5, 4, v4
	s_waitcnt lgkmcnt(0)
	v_lshlrev_b32_e32 v16, 16, v6
	v_and_b32_e32 v17, 0xffff0000, v6
	s_waitcnt vmcnt(7)
; #define LAS __attribute__((address_space(3)))
; __device__ __forceinline__ unsigned cvtpk(float lo, float hi) { f32x2 v = {lo, hi}; bf16x2_t b = __builtin_convertvector(v, bf16x2_t); return __builtin_bit_cast(unsigned, b); }
; __device__ __forceinline__ float bflo(unsigned u) { return __uint_as_float(u << 16); }
; __device__ __forceinline__ float bfhi(unsigned u) { return __uint_as_float(u & 0xffff0000u); }
; __device__ __forceinline__ void pool_unit(LAS char* lds, int pm, int g, bf16_t* Z, const bf16_t* Wt  , const float* pscale, bool dry) {
;     ...
;     for (int i = 0; i < 8; ++i) { const int id = lane + 64 * i, row = id >> 4, ch = id & 15;
;         const u32x4 ov = *(const LAS u32x4*)(lds + (32 * wid + row) * PP + ch * 16);
;         bf16_t* yp = Z + (size_t)(pm * 256 + 32 * wid + row) * ZP + ZYP + g * 128 + ch * 8;
;         if (!dry) { const u32x4 gv = *(const u32x4*)yp; u32x4 w;
;             w.x = cvtpk(bflo(ov.x) * bflo(gv.x), bfhi(ov.x) * bfhi(gv.x)); w.y = cvtpk(bflo(ov.y) * bflo(gv.y), bfhi(ov.y) * bfhi(gv.y));
;             w.z = cvtpk(bflo(ov.z) * bflo(gv.z), bfhi(ov.z) * bfhi(gv.z)); w.w = cvtpk(bflo(ov.w) * bflo(gv.w), bfhi(ov.w) * bfhi(gv.w));
;             *(u32x4*)yp = w; } }
	v_mov_b64_e32 v[10:11], v[114:115]
	v_mov_b64_e32 v[12:13], v[116:117]
	v_lshlrev_b32_e32 v18, 16, v10
	v_and_b32_e32 v19, 0xffff0000, v10
	v_pk_mul_f32 v[16:17], v[16:17], v[18:19]
	v_lshlrev_b32_e32 v10, 16, v11
	v_cvt_pk_bf16_f32 v6, v16, v17
	v_lshlrev_b32_e32 v16, 16, v7
	v_and_b32_e32 v17, 0xffff0000, v7
	v_and_b32_e32 v11, 0xffff0000, v11
	v_pk_mul_f32 v[10:11], v[16:17], v[10:11]
	v_lshlrev_b32_e32 v16, 16, v12
	v_cvt_pk_bf16_f32 v7, v10, v11
	v_lshlrev_b32_e32 v10, 16, v8
	v_and_b32_e32 v11, 0xffff0000, v8
	v_and_b32_e32 v17, 0xffff0000, v12
	v_pk_mul_f32 v[10:11], v[10:11], v[16:17]
	v_lshlrev_b32_e32 v12, 16, v13
	v_cvt_pk_bf16_f32 v8, v10, v11
	v_lshlrev_b32_e32 v10, 16, v9
	v_and_b32_e32 v11, 0xffff0000, v9
	v_and_b32_e32 v13, 0xffff0000, v13
	v_pk_mul_f32 v[10:11], v[10:11], v[12:13]
	s_nop 0
	v_cvt_pk_bf16_f32 v9, v10, v11
	global_store_dwordx4 v[14:15], v[6:9], off offset:1024
	s_nop 1
	v_or_b32_e32 v6, s1, v5
	v_mad_i64_i32 v[6:7], s[2:3], v6, s13, v[2:3]
	v_lshl_add_u64 v[6:7], v[6:7], 0, s[8:9]
	v_lshl_add_u64 v[10:11], v[6:7], 0, v[66:67]
	v_add_co_u32_e32 v14, vcc, s17, v10
	v_or_b32_e32 v5, s0, v5
	s_nop 0
	v_addc_co_u32_e32 v15, vcc, 0, v11, vcc
	s_nop 0
	v_mad_u64_u32 v[6:7], s[2:3], v5, s58, v[0:1]
	ds_read_b128 v[6:9], v6
	v_or_b32_e32 v5, 8, v4
	s_waitcnt lgkmcnt(0)
	v_lshlrev_b32_e32 v16, 16, v6
	v_and_b32_e32 v17, 0xffff0000, v6
	s_waitcnt vmcnt(6)
	v_mov_b64_e32 v[10:11], v[118:119]
	v_mov_b64_e32 v[12:13], v[120:121]
	v_lshlrev_b32_e32 v18, 16, v10
	v_and_b32_e32 v19, 0xffff0000, v10
	v_pk_mul_f32 v[16:17], v[16:17], v[18:19]
	v_lshlrev_b32_e32 v10, 16, v11
	v_cvt_pk_bf16_f32 v6, v16, v17
	v_lshlrev_b32_e32 v16, 16, v7
	v_and_b32_e32 v17, 0xffff0000, v7
	v_and_b32_e32 v11, 0xffff0000, v11
	v_pk_mul_f32 v[10:11], v[16:17], v[10:11]
	v_lshlrev_b32_e32 v16, 16, v12
	v_cvt_pk_bf16_f32 v7, v10, v11
	v_lshlrev_b32_e32 v10, 16, v8
	v_and_b32_e32 v11, 0xffff0000, v8
	v_and_b32_e32 v17, 0xffff0000, v12
	v_pk_mul_f32 v[10:11], v[10:11], v[16:17]
	v_lshlrev_b32_e32 v12, 16, v13
	v_cvt_pk_bf16_f32 v8, v10, v11
	v_lshlrev_b32_e32 v10, 16, v9
	v_and_b32_e32 v11, 0xffff0000, v9
	v_and_b32_e32 v13, 0xffff0000, v13
	v_pk_mul_f32 v[10:11], v[10:11], v[12:13]
	s_nop 0
	v_cvt_pk_bf16_f32 v9, v10, v11
	global_store_dwordx4 v[14:15], v[6:9], off offset:1024
	s_nop 1
	v_or_b32_e32 v6, s1, v5
	v_mad_i64_i32 v[6:7], s[2:3], v6, s13, v[2:3]
	v_lshl_add_u64 v[6:7], v[6:7], 0, s[8:9]
	v_lshl_add_u64 v[10:11], v[6:7], 0, v[66:67]
	v_add_co_u32_e32 v14, vcc, s17, v10
	v_or_b32_e32 v5, s0, v5
	s_nop 0
	v_addc_co_u32_e32 v15, vcc, 0, v11, vcc
	s_nop 0
	v_mad_u64_u32 v[6:7], s[2:3], v5, s58, v[0:1]
	ds_read_b128 v[6:9], v6
	v_or_b32_e32 v5, 12, v4
	s_waitcnt lgkmcnt(0)
	v_lshlrev_b32_e32 v16, 16, v6
	v_and_b32_e32 v17, 0xffff0000, v6
	s_waitcnt vmcnt(5)
	v_mov_b64_e32 v[10:11], v[122:123]
	v_mov_b64_e32 v[12:13], v[124:125]
	v_lshlrev_b32_e32 v18, 16, v10
	v_and_b32_e32 v19, 0xffff0000, v10
	v_pk_mul_f32 v[16:17], v[16:17], v[18:19]
	v_lshlrev_b32_e32 v10, 16, v11
	v_cvt_pk_bf16_f32 v6, v16, v17
	v_lshlrev_b32_e32 v16, 16, v7
	v_and_b32_e32 v17, 0xffff0000, v7
	v_and_b32_e32 v11, 0xffff0000, v11
	v_pk_mul_f32 v[10:11], v[16:17], v[10:11]
	v_lshlrev_b32_e32 v16, 16, v12
	v_cvt_pk_bf16_f32 v7, v10, v11
	v_lshlrev_b32_e32 v10, 16, v8
	v_and_b32_e32 v11, 0xffff0000, v8
	v_and_b32_e32 v17, 0xffff0000, v12
	v_pk_mul_f32 v[10:11], v[10:11], v[16:17]
	v_lshlrev_b32_e32 v12, 16, v13
	v_cvt_pk_bf16_f32 v8, v10, v11
	v_lshlrev_b32_e32 v10, 16, v9
	v_and_b32_e32 v11, 0xffff0000, v9
	v_and_b32_e32 v13, 0xffff0000, v13
	v_pk_mul_f32 v[10:11], v[10:11], v[12:13]
	s_nop 0
	v_cvt_pk_bf16_f32 v9, v10, v11
	global_store_dwordx4 v[14:15], v[6:9], off offset:1024
	s_nop 1
	v_or_b32_e32 v6, s1, v5
	v_mad_i64_i32 v[6:7], s[2:3], v6, s13, v[2:3]
	v_lshl_add_u64 v[6:7], v[6:7], 0, s[8:9]
	v_lshl_add_u64 v[10:11], v[6:7], 0, v[66:67]
	v_add_co_u32_e32 v14, vcc, s17, v10
	v_or_b32_e32 v5, s0, v5
	s_nop 0
	v_addc_co_u32_e32 v15, vcc, 0, v11, vcc
	s_nop 0
	v_mad_u64_u32 v[6:7], s[2:3], v5, s58, v[0:1]
	ds_read_b128 v[6:9], v6
	v_or_b32_e32 v5, 16, v4
	s_waitcnt lgkmcnt(0)
	v_lshlrev_b32_e32 v16, 16, v6
	v_and_b32_e32 v17, 0xffff0000, v6
	s_waitcnt vmcnt(4)
	v_mov_b64_e32 v[10:11], v[126:127]
	v_mov_b64_e32 v[12:13], v[128:129]
	v_lshlrev_b32_e32 v18, 16, v10
	v_and_b32_e32 v19, 0xffff0000, v10
	v_pk_mul_f32 v[16:17], v[16:17], v[18:19]
	v_lshlrev_b32_e32 v10, 16, v11
	v_cvt_pk_bf16_f32 v6, v16, v17
	v_lshlrev_b32_e32 v16, 16, v7
	v_and_b32_e32 v17, 0xffff0000, v7
	v_and_b32_e32 v11, 0xffff0000, v11
	v_pk_mul_f32 v[10:11], v[16:17], v[10:11]
	v_lshlrev_b32_e32 v16, 16, v12
	v_cvt_pk_bf16_f32 v7, v10, v11
	v_lshlrev_b32_e32 v10, 16, v8
	v_and_b32_e32 v11, 0xffff0000, v8
	v_and_b32_e32 v17, 0xffff0000, v12
	v_pk_mul_f32 v[10:11], v[10:11], v[16:17]
	v_lshlrev_b32_e32 v12, 16, v13
	v_cvt_pk_bf16_f32 v8, v10, v11
	v_lshlrev_b32_e32 v10, 16, v9
	v_and_b32_e32 v11, 0xffff0000, v9
	v_and_b32_e32 v13, 0xffff0000, v13
	v_pk_mul_f32 v[10:11], v[10:11], v[12:13]
	s_nop 0
	v_cvt_pk_bf16_f32 v9, v10, v11
	global_store_dwordx4 v[14:15], v[6:9], off offset:1024
	s_nop 1
	v_or_b32_e32 v6, s1, v5
	v_mad_i64_i32 v[6:7], s[2:3], v6, s13, v[2:3]
	v_lshl_add_u64 v[6:7], v[6:7], 0, s[8:9]
	v_lshl_add_u64 v[10:11], v[6:7], 0, v[66:67]
	v_add_co_u32_e32 v14, vcc, s17, v10
	v_or_b32_e32 v5, s0, v5
	s_nop 0
	v_addc_co_u32_e32 v15, vcc, 0, v11, vcc
	s_nop 0
	v_mad_u64_u32 v[6:7], s[2:3], v5, s58, v[0:1]
	ds_read_b128 v[6:9], v6
	v_or_b32_e32 v5, 20, v4
	s_waitcnt lgkmcnt(0)
; #define LAS __attribute__((address_space(3)))
; __device__ __forceinline__ unsigned cvtpk(float lo, float hi) { f32x2 v = {lo, hi}; bf16x2_t b = __builtin_convertvector(v, bf16x2_t); return __builtin_bit_cast(unsigned, b); }
; __device__ __forceinline__ float bflo(unsigned u) { return __uint_as_float(u << 16); }
; __device__ __forceinline__ float bfhi(unsigned u) { return __uint_as_float(u & 0xffff0000u); }
; __device__ __forceinline__ void pool_unit(LAS char* lds, int pm, int g, bf16_t* Z, const bf16_t* Wt  , const float* pscale, bool dry) {
;     ...
;     for (int i = 0; i < 8; ++i) { const int id = lane + 64 * i, row = id >> 4, ch = id & 15;
;         const u32x4 ov = *(const LAS u32x4*)(lds + (32 * wid + row) * PP + ch * 16);
;         bf16_t* yp = Z + (size_t)(pm * 256 + 32 * wid + row) * ZP + ZYP + g * 128 + ch * 8;
;         if (!dry) { const u32x4 gv = *(const u32x4*)yp; u32x4 w;
;             w.x = cvtpk(bflo(ov.x) * bflo(gv.x), bfhi(ov.x) * bfhi(gv.x)); w.y = cvtpk(bflo(ov.y) * bflo(gv.y), bfhi(ov.y) * bfhi(gv.y));
;             w.z = cvtpk(bflo(ov.z) * bflo(gv.z), bfhi(ov.z) * bfhi(gv.z)); w.w = cvtpk(bflo(ov.w) * bflo(gv.w), bfhi(ov.w) * bfhi(gv.w));
;             *(u32x4*)yp = w; } }
;     __syncthreads();
	v_lshlrev_b32_e32 v16, 16, v6
	v_and_b32_e32 v17, 0xffff0000, v6
	s_waitcnt vmcnt(3)
	v_mov_b64_e32 v[10:11], v[130:131]
	v_mov_b64_e32 v[12:13], v[132:133]
	v_lshlrev_b32_e32 v18, 16, v10
	v_and_b32_e32 v19, 0xffff0000, v10
	v_pk_mul_f32 v[16:17], v[16:17], v[18:19]
	v_lshlrev_b32_e32 v10, 16, v11
	v_cvt_pk_bf16_f32 v6, v16, v17
	v_lshlrev_b32_e32 v16, 16, v7
	v_and_b32_e32 v17, 0xffff0000, v7
	v_and_b32_e32 v11, 0xffff0000, v11
	v_pk_mul_f32 v[10:11], v[16:17], v[10:11]
	v_lshlrev_b32_e32 v16, 16, v12
	v_cvt_pk_bf16_f32 v7, v10, v11
	v_lshlrev_b32_e32 v10, 16, v8
	v_and_b32_e32 v11, 0xffff0000, v8
	v_and_b32_e32 v17, 0xffff0000, v12
	v_pk_mul_f32 v[10:11], v[10:11], v[16:17]
	v_lshlrev_b32_e32 v12, 16, v13
	v_cvt_pk_bf16_f32 v8, v10, v11
	v_lshlrev_b32_e32 v10, 16, v9
	v_and_b32_e32 v11, 0xffff0000, v9
	v_and_b32_e32 v13, 0xffff0000, v13
	v_pk_mul_f32 v[10:11], v[10:11], v[12:13]
	s_nop 0
	v_cvt_pk_bf16_f32 v9, v10, v11
	global_store_dwordx4 v[14:15], v[6:9], off offset:1024
	s_nop 1
	v_or_b32_e32 v6, s1, v5
	v_mad_i64_i32 v[6:7], s[2:3], v6, s13, v[2:3]
	v_lshl_add_u64 v[6:7], v[6:7], 0, s[8:9]
	v_lshl_add_u64 v[10:11], v[6:7], 0, v[66:67]
	v_add_co_u32_e32 v14, vcc, s17, v10
	v_or_b32_e32 v5, s0, v5
	s_nop 0
	v_addc_co_u32_e32 v15, vcc, 0, v11, vcc
	s_nop 0
	v_mad_u64_u32 v[6:7], s[2:3], v5, s58, v[0:1]
	ds_read_b128 v[6:9], v6
	v_or_b32_e32 v5, 24, v4
	v_or_b32_e32 v4, 28, v4
	s_waitcnt lgkmcnt(0)
	v_lshlrev_b32_e32 v16, 16, v6
	v_and_b32_e32 v17, 0xffff0000, v6
	s_waitcnt vmcnt(2)
	v_mov_b64_e32 v[10:11], v[134:135]
	v_mov_b64_e32 v[12:13], v[136:137]
	v_lshlrev_b32_e32 v18, 16, v10
	v_and_b32_e32 v19, 0xffff0000, v10
	v_pk_mul_f32 v[16:17], v[16:17], v[18:19]
	v_lshlrev_b32_e32 v10, 16, v11
	v_cvt_pk_bf16_f32 v6, v16, v17
	v_lshlrev_b32_e32 v16, 16, v7
	v_and_b32_e32 v17, 0xffff0000, v7
	v_and_b32_e32 v11, 0xffff0000, v11
	v_pk_mul_f32 v[10:11], v[16:17], v[10:11]
	v_lshlrev_b32_e32 v16, 16, v12
	v_cvt_pk_bf16_f32 v7, v10, v11
	v_lshlrev_b32_e32 v10, 16, v8
	v_and_b32_e32 v11, 0xffff0000, v8
	v_and_b32_e32 v17, 0xffff0000, v12
	v_pk_mul_f32 v[10:11], v[10:11], v[16:17]
	v_lshlrev_b32_e32 v12, 16, v13
	v_cvt_pk_bf16_f32 v8, v10, v11
	v_lshlrev_b32_e32 v10, 16, v9
	v_and_b32_e32 v11, 0xffff0000, v9
	v_and_b32_e32 v13, 0xffff0000, v13
	v_pk_mul_f32 v[10:11], v[10:11], v[12:13]
	s_nop 0
	v_cvt_pk_bf16_f32 v9, v10, v11
	global_store_dwordx4 v[14:15], v[6:9], off offset:1024
	s_nop 1
	v_or_b32_e32 v6, s1, v5
	v_mad_i64_i32 v[6:7], s[2:3], v6, s13, v[2:3]
	v_lshl_add_u64 v[6:7], v[6:7], 0, s[8:9]
	v_lshl_add_u64 v[10:11], v[6:7], 0, v[66:67]
	v_add_co_u32_e32 v14, vcc, s17, v10
	v_or_b32_e32 v5, s0, v5
	s_nop 0
	v_addc_co_u32_e32 v15, vcc, 0, v11, vcc
	s_nop 0
	v_mad_u64_u32 v[6:7], s[2:3], v5, s58, v[0:1]
	ds_read_b128 v[6:9], v6
	v_or_b32_e32 v5, s1, v4
	v_mad_i64_i32 v[2:3], s[2:3], v5, s13, v[2:3]
	v_lshl_add_u64 v[2:3], v[2:3], 0, s[8:9]
	s_waitcnt lgkmcnt(0)
	v_lshlrev_b32_e32 v16, 16, v6
	v_and_b32_e32 v17, 0xffff0000, v6
	s_waitcnt vmcnt(1)
	v_mov_b64_e32 v[10:11], v[138:139]
	v_mov_b64_e32 v[12:13], v[140:141]
	v_lshlrev_b32_e32 v18, 16, v10
	v_and_b32_e32 v19, 0xffff0000, v10
	v_pk_mul_f32 v[16:17], v[16:17], v[18:19]
	v_lshlrev_b32_e32 v10, 16, v11
	v_cvt_pk_bf16_f32 v6, v16, v17
	v_lshlrev_b32_e32 v16, 16, v7
	v_and_b32_e32 v17, 0xffff0000, v7
	v_and_b32_e32 v11, 0xffff0000, v11
	v_pk_mul_f32 v[10:11], v[16:17], v[10:11]
	v_lshlrev_b32_e32 v16, 16, v12
	v_cvt_pk_bf16_f32 v7, v10, v11
	v_lshlrev_b32_e32 v10, 16, v8
	v_and_b32_e32 v11, 0xffff0000, v8
	v_and_b32_e32 v17, 0xffff0000, v12
	v_pk_mul_f32 v[10:11], v[10:11], v[16:17]
	v_lshlrev_b32_e32 v12, 16, v13
	v_cvt_pk_bf16_f32 v8, v10, v11
	v_lshlrev_b32_e32 v10, 16, v9
	v_and_b32_e32 v11, 0xffff0000, v9
	v_and_b32_e32 v13, 0xffff0000, v13
	v_pk_mul_f32 v[10:11], v[10:11], v[12:13]
	s_nop 0
	v_cvt_pk_bf16_f32 v9, v10, v11
	global_store_dwordx4 v[14:15], v[6:9], off offset:1024
	s_nop 1
	v_lshl_add_u64 v[6:7], v[2:3], 0, v[66:67]
	v_add_co_u32_e32 v10, vcc, s17, v6
	v_or_b32_e32 v2, s0, v4
	s_nop 0
	v_addc_co_u32_e32 v11, vcc, 0, v7, vcc
	s_nop 0
	v_mad_u64_u32 v[2:3], s[0:1], v2, s58, v[0:1]
	ds_read_b128 v[2:5], v2
	s_waitcnt lgkmcnt(0)
	v_lshlrev_b32_e32 v12, 16, v2
	v_and_b32_e32 v13, 0xffff0000, v2
	s_waitcnt vmcnt(0)
	v_mov_b64_e32 v[6:7], v[142:143]
	v_mov_b64_e32 v[8:9], v[144:145]
	v_lshlrev_b32_e32 v14, 16, v6
	v_and_b32_e32 v15, 0xffff0000, v6
	v_pk_mul_f32 v[12:13], v[12:13], v[14:15]
	v_lshlrev_b32_e32 v6, 16, v7
	v_cvt_pk_bf16_f32 v2, v12, v13
	v_lshlrev_b32_e32 v12, 16, v3
	v_and_b32_e32 v13, 0xffff0000, v3
	v_and_b32_e32 v7, 0xffff0000, v7
	v_pk_mul_f32 v[6:7], v[12:13], v[6:7]
	v_lshlrev_b32_e32 v12, 16, v8
	v_cvt_pk_bf16_f32 v3, v6, v7
	v_lshlrev_b32_e32 v6, 16, v4
	v_and_b32_e32 v7, 0xffff0000, v4
	v_and_b32_e32 v13, 0xffff0000, v8
	v_pk_mul_f32 v[6:7], v[6:7], v[12:13]
	v_lshlrev_b32_e32 v8, 16, v9
	v_cvt_pk_bf16_f32 v4, v6, v7
	v_lshlrev_b32_e32 v6, 16, v5
	v_and_b32_e32 v7, 0xffff0000, v5
	v_and_b32_e32 v9, 0xffff0000, v9
	v_pk_mul_f32 v[6:7], v[6:7], v[8:9]
	s_nop 0
	v_cvt_pk_bf16_f32 v5, v6, v7
	global_store_dwordx4 v[10:11], v[2:5], off offset:1024
	s_barrier

; #define LAS __attribute__((address_space(3)))
; __device__ __forceinline__ unsigned cvtpk(float lo, float hi) { f32x2 v = {lo, hi}; bf16x2_t b = __builtin_convertvector(v, bf16x2_t); return __builtin_bit_cast(unsigned, b); }
; __device__ __forceinline__ float bflo(unsigned u) { return __uint_as_float(u << 16); }
; __device__ __forceinline__ float bfhi(unsigned u) { return __uint_as_float(u & 0xffff0000u); }
; __device__ __forceinline__ float frcp(float x) { return __builtin_amdgcn_rcpf(x); }
; __device__ __forceinline__ void pool_unit(LAS char* lds, int pm, int g, bf16_t* Z, const bf16_t* Wt  , const float* pscale, bool dry) {
;     ...
;         for (int i = 0; i < 16; ++i) {
;             const int t = ts + i;
;             int l2 = t - half; if (l2 < 0) l2 = 0; int h2 = t + half; if (h2 > L) h2 = L;
;             const u32x2 ut = *(const LAS u32x2*)(uc + (t - t0 + 8) * PP);
;             const float rc = frcp((float)(h2 - l2));
;             u32x2 w; w.x = cvtpk(s0 * rc - bflo(ut.x), s1 * rc - bfhi(ut.x)); w.y = cvtpk(s2 * rc - bflo(ut.y), s3 * rc - bfhi(ut.y));
;             *(LAS u32x2*)(lds + (rsg * 16 + i) * PP + cg * 8) = w;
;             if (t + half < L) { const u32x2 v = *(const LAS u32x2*)(uc + (t + half - t0 + 8) * PP); s0 += bflo(v.x); s1 += bfhi(v.x); s2 += bflo(v.y); s3 += bfhi(v.y); }
;             if (t - half >= 0) { const u32x2 v = *(const LAS u32x2*)(uc + (t - half - t0 + 8) * PP); s0 -= bflo(v.x); s1 -= bfhi(v.x); s2 -= bflo(v.y); s3 -= bfhi(v.y); }
.LBB0_696:
	v_add_u32_e32 v28, s3, v23
	v_add_u32_e32 v29, s25, v23
	v_max_i32_e32 v26, 0, v28
	v_min_i32_e32 v27, s24, v29
	v_sub_u32_e32 v26, v27, v26
	v_cvt_f32_i32_e32 v30, v26
	v_add_u32_e32 v25, s28, v0
	v_add_u32_e32 v139, s28, v24
	v_add_u32_e32 v140, s28, v22
	v_add_u32_e32 v138, 0x12980, v25
	v_add_u32_e32 v139, 0x12980, v139
	v_add_u32_e32 v140, 0x12980, v140
	ds_read_b64 v[114:115], v138
	ds_read_b64 v[116:117], v139
	ds_read_b64 v[118:119], v140
	ds_read_b64 v[120:121], v138 offset:272
	ds_read_b64 v[122:123], v139 offset:272
	ds_read_b64 v[124:125], v140 offset:272
	ds_read_b64 v[126:127], v138 offset:544
	ds_read_b64 v[128:129], v139 offset:544
	ds_read_b64 v[130:131], v140 offset:544
	ds_read_b64 v[132:133], v138 offset:816
	ds_read_b64 v[134:135], v139 offset:816
	ds_read_b64 v[136:137], v140 offset:816
	s_waitcnt lgkmcnt(0)
	v_add_u32_e32 v26, 0x12980, v25
	v_mov_b64_e32 v[26:27], v[114:115]
	v_rcp_iflag_f32_e32 v30, v30
	v_cmp_gt_i32_e32 vcc, s24, v29
	v_lshlrev_b32_e32 v32, 16, v26
	v_pk_mul_f32 v[34:35], v[20:21], v[30:31] op_sel_hi:[1,0]
	v_and_b32_e32 v33, 0xffff0000, v26
	v_pk_add_f32 v[32:33], v[34:35], v[32:33] op_sel:[1,0] op_sel_hi:[0,1] neg_lo:[0,1] neg_hi:[0,1]
	v_cvt_pk_bf16_f32 v26, v32, v33
	v_pk_mul_f32 v[30:31], v[18:19], v[30:31] op_sel_hi:[1,0]
	v_lshlrev_b32_e32 v32, 16, v27
	v_and_b32_e32 v33, 0xffff0000, v27
	v_pk_add_f32 v[30:31], v[30:31], v[32:33] op_sel:[1,0] op_sel_hi:[0,1] neg_lo:[0,1] neg_hi:[0,1]
	v_cvt_pk_bf16_f32 v27, v30, v31
	ds_write_b64 v25, v[26:27] offset:4352
	v_add_u32_e32 v26, s28, v24
	s_and_saveexec_b64 s[0:1], vcc
	s_cbranch_execz .LBB0_698
	v_add_u32_e32 v27, 0x12980, v26
	v_mov_b64_e32 v[30:31], v[116:117]
	v_and_b32_e32 v32, 0xffff0000, v30
	v_lshlrev_b32_e32 v33, 16, v30
	v_and_b32_e32 v30, 0xffff0000, v31
	v_lshlrev_b32_e32 v31, 16, v31
	v_pk_add_f32 v[20:21], v[20:21], v[32:33]
	v_pk_add_f32 v[18:19], v[18:19], v[30:31]
.LBB0_698:
	s_or_b64 exec, exec, s[0:1]
	v_cmp_lt_i32_e32 vcc, -1, v28
	v_add_u32_e32 v27, s28, v22
	s_and_saveexec_b64 s[0:1], vcc
	s_cbranch_execz .LBB0_700
	v_add_u32_e32 v30, 0x12980, v27
	v_mov_b64_e32 v[30:31], v[118:119]
	v_and_b32_e32 v32, 0xffff0000, v30
	v_lshlrev_b32_e32 v33, 16, v30
	v_and_b32_e32 v30, 0xffff0000, v31
	v_lshlrev_b32_e32 v31, 16, v31
	v_pk_add_f32 v[20:21], v[20:21], v[32:33] neg_lo:[0,1] neg_hi:[0,1]
	v_pk_add_f32 v[18:19], v[18:19], v[30:31] neg_lo:[0,1] neg_hi:[0,1]
.LBB0_700:
	s_or_b64 exec, exec, s[0:1]
	v_add_u32_e32 v30, 1, v28
	v_add_u32_e32 v39, 1, v29
	v_max_i32_e32 v31, 0, v30
	v_min_i32_e32 v32, s24, v39
	v_sub_u32_e32 v31, v32, v31
	v_cvt_f32_i32_e32 v31, v31
	v_add_u32_e32 v33, 0x12a90, v25
	v_mov_b64_e32 v[32:33], v[120:121]
	v_cmp_gt_i32_e32 vcc, s24, v39
	v_rcp_iflag_f32_e32 v34, v31
	v_lshlrev_b32_e32 v36, 16, v32
	v_and_b32_e32 v37, 0xffff0000, v32
	v_pk_mul_f32 v[48:49], v[20:21], v[34:35] op_sel_hi:[1,0]
	v_pk_mul_f32 v[34:35], v[18:19], v[34:35] op_sel_hi:[1,0]
	v_pk_add_f32 v[36:37], v[48:49], v[36:37] op_sel:[1,0] op_sel_hi:[0,1] neg_lo:[0,1] neg_hi:[0,1]
	v_cvt_pk_bf16_f32 v32, v36, v37
	v_lshlrev_b32_e32 v36, 16, v33
	v_and_b32_e32 v37, 0xffff0000, v33
	v_pk_add_f32 v[34:35], v[34:35], v[36:37] op_sel:[1,0] op_sel_hi:[0,1] neg_lo:[0,1] neg_hi:[0,1]
	v_cvt_pk_bf16_f32 v33, v34, v35
	ds_write_b64 v25, v[32:33] offset:4624
	s_and_saveexec_b64 s[0:1], vcc
	s_cbranch_execz .LBB0_702
	v_add_u32_e32 v31, 0x12a90, v26
	v_mov_b64_e32 v[32:33], v[122:123]
	v_and_b32_e32 v34, 0xffff0000, v32
	v_lshlrev_b32_e32 v35, 16, v32
	v_and_b32_e32 v32, 0xffff0000, v33
	v_lshlrev_b32_e32 v33, 16, v33
	v_pk_add_f32 v[20:21], v[20:21], v[34:35]
	v_pk_add_f32 v[18:19], v[18:19], v[32:33]
; #define LAS __attribute__((address_space(3)))
; __device__ __forceinline__ unsigned cvtpk(float lo, float hi) { f32x2 v = {lo, hi}; bf16x2_t b = __builtin_convertvector(v, bf16x2_t); return __builtin_bit_cast(unsigned, b); }
; __device__ __forceinline__ float bflo(unsigned u) { return __uint_as_float(u << 16); }
; __device__ __forceinline__ float bfhi(unsigned u) { return __uint_as_float(u & 0xffff0000u); }
; __device__ __forceinline__ float frcp(float x) { return __builtin_amdgcn_rcpf(x); }
; __device__ __forceinline__ void pool_unit(LAS char* lds, int pm, int g, bf16_t* Z, const bf16_t* Wt  , const float* pscale, bool dry) {
;     ...
;         for (int i = 0; i < 16; ++i) {
;             const int t = ts + i;
;             int l2 = t - half; if (l2 < 0) l2 = 0; int h2 = t + half; if (h2 > L) h2 = L;
;             const u32x2 ut = *(const LAS u32x2*)(uc + (t - t0 + 8) * PP);
;             const float rc = frcp((float)(h2 - l2));
;             u32x2 w; w.x = cvtpk(s0 * rc - bflo(ut.x), s1 * rc - bfhi(ut.x)); w.y = cvtpk(s2 * rc - bflo(ut.y), s3 * rc - bfhi(ut.y));
;             *(LAS u32x2*)(lds + (rsg * 16 + i) * PP + cg * 8) = w;
;             if (t + half < L) { const u32x2 v = *(const LAS u32x2*)(uc + (t + half - t0 + 8) * PP); s0 += bflo(v.x); s1 += bfhi(v.x); s2 += bflo(v.y); s3 += bfhi(v.y); }
;             if (t - half >= 0) { const u32x2 v = *(const LAS u32x2*)(uc + (t - half - t0 + 8) * PP); s0 -= bflo(v.x); s1 -= bfhi(v.x); s2 -= bflo(v.y); s3 -= bfhi(v.y); }
;         }
.LBB0_702:
	s_or_b64 exec, exec, s[0:1]
	v_cmp_lt_i32_e32 vcc, -1, v30
	s_and_saveexec_b64 s[0:1], vcc
	s_cbranch_execz .LBB0_704
	v_add_u32_e32 v30, 0x12a90, v27
	v_mov_b64_e32 v[30:31], v[124:125]
	v_and_b32_e32 v32, 0xffff0000, v30
	v_lshlrev_b32_e32 v33, 16, v30
	v_and_b32_e32 v30, 0xffff0000, v31
	v_lshlrev_b32_e32 v31, 16, v31
	v_pk_add_f32 v[20:21], v[20:21], v[32:33] neg_lo:[0,1] neg_hi:[0,1]
	v_pk_add_f32 v[18:19], v[18:19], v[30:31] neg_lo:[0,1] neg_hi:[0,1]
.LBB0_704:
	s_or_b64 exec, exec, s[0:1]
	v_add_u32_e32 v30, 2, v28
	v_add_u32_e32 v39, 2, v29
	v_max_i32_e32 v31, 0, v30
	v_min_i32_e32 v32, s24, v39
	v_sub_u32_e32 v31, v32, v31
	v_cvt_f32_i32_e32 v31, v31
	v_add_u32_e32 v33, 0x12ba0, v25
	v_mov_b64_e32 v[32:33], v[126:127]
	v_cmp_gt_i32_e32 vcc, s24, v39
	v_rcp_iflag_f32_e32 v34, v31
	v_lshlrev_b32_e32 v36, 16, v32
	v_and_b32_e32 v37, 0xffff0000, v32
	v_pk_mul_f32 v[48:49], v[20:21], v[34:35] op_sel_hi:[1,0]
	v_pk_mul_f32 v[34:35], v[18:19], v[34:35] op_sel_hi:[1,0]
	v_pk_add_f32 v[36:37], v[48:49], v[36:37] op_sel:[1,0] op_sel_hi:[0,1] neg_lo:[0,1] neg_hi:[0,1]
	v_cvt_pk_bf16_f32 v32, v36, v37
	v_lshlrev_b32_e32 v36, 16, v33
	v_and_b32_e32 v37, 0xffff0000, v33
	v_pk_add_f32 v[34:35], v[34:35], v[36:37] op_sel:[1,0] op_sel_hi:[0,1] neg_lo:[0,1] neg_hi:[0,1]
	v_cvt_pk_bf16_f32 v33, v34, v35
	ds_write_b64 v25, v[32:33] offset:4896
	s_and_saveexec_b64 s[0:1], vcc
	s_cbranch_execz .LBB0_706
	v_add_u32_e32 v31, 0x12ba0, v26
	v_mov_b64_e32 v[32:33], v[128:129]
	v_and_b32_e32 v34, 0xffff0000, v32
	v_lshlrev_b32_e32 v35, 16, v32
	v_and_b32_e32 v32, 0xffff0000, v33
	v_lshlrev_b32_e32 v33, 16, v33
	v_pk_add_f32 v[20:21], v[20:21], v[34:35]
	v_pk_add_f32 v[18:19], v[18:19], v[32:33]
.LBB0_706:
	s_or_b64 exec, exec, s[0:1]
	v_cmp_lt_i32_e32 vcc, -1, v30
	s_and_saveexec_b64 s[0:1], vcc
	s_cbranch_execz .LBB0_708
	v_add_u32_e32 v30, 0x12ba0, v27
	v_mov_b64_e32 v[30:31], v[130:131]
	v_and_b32_e32 v32, 0xffff0000, v30
	v_lshlrev_b32_e32 v33, 16, v30
	v_and_b32_e32 v30, 0xffff0000, v31
	v_lshlrev_b32_e32 v31, 16, v31
	v_pk_add_f32 v[20:21], v[20:21], v[32:33] neg_lo:[0,1] neg_hi:[0,1]
	v_pk_add_f32 v[18:19], v[18:19], v[30:31] neg_lo:[0,1] neg_hi:[0,1]
.LBB0_708:
	s_or_b64 exec, exec, s[0:1]
	v_add_u32_e32 v28, 3, v28
	v_add_u32_e32 v29, 3, v29
	v_max_i32_e32 v30, 0, v28
	v_min_i32_e32 v31, s24, v29
	v_sub_u32_e32 v30, v31, v30
	v_cvt_f32_i32_e32 v33, v30
	v_add_u32_e32 v32, 0x12cb0, v25
	v_mov_b64_e32 v[30:31], v[132:133]
	v_cmp_gt_i32_e32 vcc, s24, v29
	v_rcp_iflag_f32_e32 v32, v33
	v_lshlrev_b32_e32 v34, 16, v30
	v_and_b32_e32 v35, 0xffff0000, v30
	v_pk_mul_f32 v[36:37], v[20:21], v[32:33] op_sel_hi:[1,0]
	v_pk_mul_f32 v[32:33], v[18:19], v[32:33] op_sel_hi:[1,0]
	v_pk_add_f32 v[34:35], v[36:37], v[34:35] op_sel:[1,0] op_sel_hi:[0,1] neg_lo:[0,1] neg_hi:[0,1]
	v_cvt_pk_bf16_f32 v30, v34, v35
	v_lshlrev_b32_e32 v34, 16, v31
	v_and_b32_e32 v35, 0xffff0000, v31
	v_pk_add_f32 v[32:33], v[32:33], v[34:35] op_sel:[1,0] op_sel_hi:[0,1] neg_lo:[0,1] neg_hi:[0,1]
	v_cvt_pk_bf16_f32 v31, v32, v33
	ds_write_b64 v25, v[30:31] offset:5168
	s_and_saveexec_b64 s[0:1], vcc
	s_cbranch_execz .LBB0_710
	v_add_u32_e32 v25, 0x12cb0, v26
	v_mov_b64_e32 v[30:31], v[134:135]
	v_and_b32_e32 v32, 0xffff0000, v30
	v_lshlrev_b32_e32 v33, 16, v30
	v_and_b32_e32 v30, 0xffff0000, v31
	v_lshlrev_b32_e32 v31, 16, v31
	v_pk_add_f32 v[20:21], v[20:21], v[32:33]
	v_pk_add_f32 v[18:19], v[18:19], v[30:31]
.LBB0_710:
	s_or_b64 exec, exec, s[0:1]
	v_cmp_lt_i32_e32 vcc, -1, v28
	s_and_saveexec_b64 s[0:1], vcc
	s_cbranch_execz .LBB0_695
	v_add_u32_e32 v25, 0x12cb0, v27
	v_mov_b64_e32 v[26:27], v[136:137]
	v_and_b32_e32 v28, 0xffff0000, v26
	v_lshlrev_b32_e32 v29, 16, v26
	v_and_b32_e32 v26, 0xffff0000, v27
	v_lshlrev_b32_e32 v27, 16, v27
	v_pk_add_f32 v[20:21], v[20:21], v[28:29] neg_lo:[0,1] neg_hi:[0,1]
	v_pk_add_f32 v[18:19], v[18:19], v[26:27] neg_lo:[0,1] neg_hi:[0,1]
	s_branch .LBB0_695
